# S5 full-pass scan loop: recurrence step as packed mul / fma (mixed negate) / add, 6 VALU per step instead of 9-11
# speedup vs baseline: 1.0037x; 1.0009x over previous
.LBB0_439:
	ds_read2_b32 v[122:123], v83 offset1:68
	ds_read2_b32 v[124:125], v83 offset0:136 offset1:204
	v_add_u32_e32 v121, 0x400, v83
	ds_read2_b32 v[126:127], v121 offset0:16 offset1:84
	ds_read2_b32 v[128:129], v121 offset0:152 offset1:220
	s_add_i32 s2, s2, 8
	s_waitcnt lgkmcnt(3)
	v_lshlrev_b32_e32 v136, 16, v122
	v_pk_mul_f32 v[134:135], v[96:97], v[92:93] op_sel:[0,1] op_sel_hi:[1,0]
	v_and_b32_e32 v137, 0xffff0000, v122
	v_pk_fma_f32 v[134:135], v[94:95], v[92:93], v[134:135] neg_lo:[0,0,1]
	s_nop 0
	v_pk_add_f32 v[92:93], v[134:135], v[136:137]
	v_lshlrev_b32_e32 v136, 16, v123
	v_pk_mul_f32 v[134:135], v[96:97], v[92:93] op_sel:[0,1] op_sel_hi:[1,0]
	v_and_b32_e32 v137, 0xffff0000, v123
	v_pk_fma_f32 v[134:135], v[94:95], v[92:93], v[134:135] neg_lo:[0,0,1]
	v_cvt_pk_bf16_f32 v130, v92, v93
	v_pk_add_f32 v[92:93], v[134:135], v[136:137]
	s_nop 0
	v_cvt_pk_bf16_f32 v131, v92, v93
	ds_write2_b32 v83, v130, v131 offset1:68
	s_waitcnt lgkmcnt(3)
	v_lshlrev_b32_e32 v136, 16, v124
	v_pk_mul_f32 v[134:135], v[96:97], v[92:93] op_sel:[0,1] op_sel_hi:[1,0]
	v_and_b32_e32 v137, 0xffff0000, v124
	v_pk_fma_f32 v[134:135], v[94:95], v[92:93], v[134:135] neg_lo:[0,0,1]
	s_nop 0
	v_pk_add_f32 v[92:93], v[134:135], v[136:137]
	v_lshlrev_b32_e32 v136, 16, v125
	v_pk_mul_f32 v[134:135], v[96:97], v[92:93] op_sel:[0,1] op_sel_hi:[1,0]
	v_and_b32_e32 v137, 0xffff0000, v125
	v_pk_fma_f32 v[134:135], v[94:95], v[92:93], v[134:135] neg_lo:[0,0,1]
	v_cvt_pk_bf16_f32 v132, v92, v93
	v_pk_add_f32 v[92:93], v[134:135], v[136:137]
	s_nop 0
	v_cvt_pk_bf16_f32 v133, v92, v93
	ds_write2_b32 v83, v132, v133 offset0:136 offset1:204
	s_waitcnt lgkmcnt(3)
	v_lshlrev_b32_e32 v136, 16, v126
	v_pk_mul_f32 v[134:135], v[96:97], v[92:93] op_sel:[0,1] op_sel_hi:[1,0]
	v_and_b32_e32 v137, 0xffff0000, v126
	v_pk_fma_f32 v[134:135], v[94:95], v[92:93], v[134:135] neg_lo:[0,0,1]
	s_nop 0
	v_pk_add_f32 v[92:93], v[134:135], v[136:137]
	v_lshlrev_b32_e32 v136, 16, v127
	v_pk_mul_f32 v[134:135], v[96:97], v[92:93] op_sel:[0,1] op_sel_hi:[1,0]
	v_and_b32_e32 v137, 0xffff0000, v127
	v_pk_fma_f32 v[134:135], v[94:95], v[92:93], v[134:135] neg_lo:[0,0,1]
	v_cvt_pk_bf16_f32 v130, v92, v93
	v_pk_add_f32 v[92:93], v[134:135], v[136:137]
	s_nop 0
	v_cvt_pk_bf16_f32 v131, v92, v93
	ds_write2_b32 v121, v130, v131 offset0:16 offset1:84
	s_waitcnt lgkmcnt(3)
	v_lshlrev_b32_e32 v136, 16, v128
	v_pk_mul_f32 v[134:135], v[96:97], v[92:93] op_sel:[0,1] op_sel_hi:[1,0]
	v_and_b32_e32 v137, 0xffff0000, v128
	v_pk_fma_f32 v[134:135], v[94:95], v[92:93], v[134:135] neg_lo:[0,0,1]
	s_nop 0
	v_pk_add_f32 v[92:93], v[134:135], v[136:137]
	v_lshlrev_b32_e32 v136, 16, v129
	v_pk_mul_f32 v[134:135], v[96:97], v[92:93] op_sel:[0,1] op_sel_hi:[1,0]
	v_and_b32_e32 v137, 0xffff0000, v129
	v_pk_fma_f32 v[134:135], v[94:95], v[92:93], v[134:135] neg_lo:[0,0,1]
	v_cvt_pk_bf16_f32 v132, v92, v93
	v_pk_add_f32 v[92:93], v[134:135], v[136:137]
	s_nop 0
	v_cvt_pk_bf16_f32 v133, v92, v93
	v_add_u32_e32 v83, 0x880, v83
	s_cmp_lt_u32 s2, 24
	ds_write2_b32 v121, v132, v133 offset0:152 offset1:220
	s_cbranch_scc1 .LBB0_439
	s_waitcnt lgkmcnt(0)
	ds_read_b128 v[122:125], v117 offset:32768
	ds_read_b128 v[126:129], v117 offset:32832
	v_or_b32_e32 v83, s14, v78
	v_mad_u32_u24 v83, v83, s15, v120
	s_mov_b32 s14, 32
	s_waitcnt lgkmcnt(1)
	v_mfma_f32_16x16x32_bf16 v[122:125], v[52:55], v[122:125], v[0:3]
	s_mov_b64 s[4:5], 0
	s_waitcnt lgkmcnt(0)
	v_mfma_f32_16x16x32_bf16 v[122:125], v[48:51], v[126:129], v[122:125]
	ds_read_b128 v[126:129], v117 offset:32896
	s_waitcnt lgkmcnt(0)
	v_mfma_f32_16x16x32_bf16 v[122:125], v[44:47], v[126:129], v[122:125]
	ds_read_b128 v[126:129], v117 offset:32960
	s_waitcnt lgkmcnt(0)
	v_mfma_f32_16x16x32_bf16 v[122:125], v[40:43], v[126:129], v[122:125]
	v_lshlrev_b32_e32 v126, 16, v102
	v_and_b32_e32 v127, 0xffff0000, v102
	s_nop 5
	v_pk_fma_f32 v[122:123], v[4:5], v[126:127], v[122:123]
	s_nop 0
	v_mul_f32_e32 v102, 0x3d372713, v122
	v_mul_f32_e32 v102, v122, v102
	v_fma_f32 v102, v122, v102, v122
	v_mul_f32_e32 v102, 0x3f4c422a, v102
	v_add_f32_e32 v102, v102, v102
	v_mul_f32_e32 v102, 0xbfb8aa3b, v102
	v_exp_f32_e32 v126, v102
	v_mul_f32_e32 v102, 0x3d372713, v123
	v_mul_f32_e32 v102, v123, v102
	v_fma_f32 v102, v123, v102, v123
	v_mul_f32_e32 v102, 0x3f4c422a, v102
	v_add_f32_e32 v102, v102, v102
	v_mul_f32_e32 v102, 0xbfb8aa3b, v102
	v_exp_f32_e32 v127, v102
	s_nop 0
	v_pk_add_f32 v[126:127], v[126:127], 1.0 op_sel_hi:[1,0]
	s_nop 0
	v_rcp_f32_e32 v127, v127
	v_rcp_f32_e32 v126, v126
	v_lshlrev_b32_e32 v102, 16, v103
	v_and_b32_e32 v103, 0xffff0000, v103
	v_pk_fma_f32 v[102:103], v[6:7], v[102:103], v[124:125]
	v_pk_mul_f32 v[122:123], v[122:123], v[126:127]
	v_mul_f32_e32 v121, 0x3d372713, v102
	v_mul_f32_e32 v121, v102, v121
	v_fma_f32 v121, v102, v121, v102
	v_mul_f32_e32 v121, 0x3f4c422a, v121
	v_add_f32_e32 v121, v121, v121
	v_mul_f32_e32 v121, 0xbfb8aa3b, v121
	v_exp_f32_e32 v124, v121
	v_mul_f32_e32 v121, 0x3d372713, v103
	v_mul_f32_e32 v121, v103, v121
	v_fma_f32 v121, v103, v121, v103
	v_mul_f32_e32 v121, 0x3f4c422a, v121
	v_add_f32_e32 v121, v121, v121
	v_mul_f32_e32 v121, 0xbfb8aa3b, v121
	v_exp_f32_e32 v125, v121
	v_cvt_pk_bf16_f32 v122, v122, v123
	v_pk_add_f32 v[124:125], v[124:125], 1.0 op_sel_hi:[1,0]
	s_nop 0
	v_rcp_f32_e32 v125, v125
	v_rcp_f32_e32 v124, v124
	s_nop 0
	v_pk_mul_f32 v[102:103], v[102:103], v[124:125]
	s_nop 0
	v_cvt_pk_bf16_f32 v123, v102, v103
	ds_write_b64 v83, v[122:123]
	ds_read_b128 v[122:125], v117 offset:37120
	ds_read_b128 v[126:129], v117 offset:37184
	s_waitcnt lgkmcnt(1)
	v_mfma_f32_16x16x32_bf16 v[122:125], v[52:55], v[122:125], v[0:3]
	v_lshlrev_b32_e32 v102, 16, v100
	v_and_b32_e32 v103, 0xffff0000, v100
	s_waitcnt lgkmcnt(0)
	v_mfma_f32_16x16x32_bf16 v[122:125], v[48:51], v[126:129], v[122:125]
	ds_read_b128 v[126:129], v117 offset:37248
	s_waitcnt lgkmcnt(0)
	v_mfma_f32_16x16x32_bf16 v[122:125], v[44:47], v[126:129], v[122:125]
	ds_read_b128 v[126:129], v117 offset:37312
	s_waitcnt lgkmcnt(0)
	v_mfma_f32_16x16x32_bf16 v[122:125], v[40:43], v[126:129], v[122:125]
	s_nop 7
	v_pk_fma_f32 v[102:103], v[4:5], v[102:103], v[122:123]
	s_nop 0
	v_mul_f32_e32 v100, 0x3d372713, v102
	v_mul_f32_e32 v100, v102, v100
	v_fma_f32 v100, v102, v100, v102
	v_mul_f32_e32 v100, 0x3f4c422a, v100
	v_add_f32_e32 v100, v100, v100
	v_mul_f32_e32 v100, 0xbfb8aa3b, v100
	v_exp_f32_e32 v122, v100
	v_mul_f32_e32 v100, 0x3d372713, v103
	v_mul_f32_e32 v100, v103, v100
	v_fma_f32 v100, v103, v100, v103
	v_mul_f32_e32 v100, 0x3f4c422a, v100
	v_add_f32_e32 v100, v100, v100
	v_mul_f32_e32 v100, 0xbfb8aa3b, v100
	v_exp_f32_e32 v123, v100
	s_nop 0
	v_pk_add_f32 v[122:123], v[122:123], 1.0 op_sel_hi:[1,0]
	s_nop 0
	v_rcp_f32_e32 v123, v123
	v_rcp_f32_e32 v122, v122
	v_lshlrev_b32_e32 v100, 16, v101
	v_and_b32_e32 v101, 0xffff0000, v101
	v_pk_fma_f32 v[100:101], v[6:7], v[100:101], v[124:125]
	v_pk_mul_f32 v[102:103], v[102:103], v[122:123]
	v_mul_f32_e32 v121, 0x3d372713, v100
	v_mul_f32_e32 v121, v100, v121
	v_fma_f32 v121, v100, v121, v100
	v_mul_f32_e32 v121, 0x3f4c422a, v121
	v_add_f32_e32 v121, v121, v121
	v_mul_f32_e32 v121, 0xbfb8aa3b, v121
	v_exp_f32_e32 v122, v121
	v_mul_f32_e32 v121, 0x3d372713, v101
	v_mul_f32_e32 v121, v101, v121
	v_fma_f32 v121, v101, v121, v101
	v_mul_f32_e32 v121, 0x3f4c422a, v121
	v_add_f32_e32 v121, v121, v121
	v_mul_f32_e32 v121, 0xbfb8aa3b, v121
	v_exp_f32_e32 v123, v121
	v_cvt_pk_bf16_f32 v102, v102, v103
	v_pk_add_f32 v[122:123], v[122:123], 1.0 op_sel_hi:[1,0]
	s_nop 0
	v_rcp_f32_e32 v123, v123
	v_rcp_f32_e32 v122, v122
	s_nop 0
	v_pk_mul_f32 v[100:101], v[100:101], v[122:123]
	s_and_b64 vcc, exec, s[12:13]
	v_cvt_pk_bf16_f32 v103, v100, v101
	ds_write_b64 v83, v[102:103] offset:8448
	s_nop 7
	s_cbranch_vccz .LBB0_438
	s_and_b64 vcc, exec, s[24:25]
	s_cbranch_vccz .LBB0_432
	s_ashr_i32 s29, s28, 31
	s_lshl_b64 s[2:3], s[28:29], 8
	v_lshl_add_u64 v[4:5], v[88:89], 0, s[2:3]
	v_add_co_u32_e32 v6, vcc, 0x645c000, v4
	s_nop 1
	v_addc_co_u32_e32 v7, vcc, 0, v5, vcc
	v_add_co_u32_e32 v4, vcc, 0x667c000, v4
	global_store_dword v[6:7], v92, off
	s_nop 0
	v_addc_co_u32_e32 v5, vcc, 0, v5, vcc
	global_store_dword v[4:5], v93, off
	s_branch .LBB0_432
